# P3 gating loop hand-written: all loads one unit ahead into a second register set, LDS gain table, double-buffered layer-norm tile, DPP quad reductions
# speedup vs baseline: 1.0104x; 1.0074x over previous
; __device__ __forceinline__ float bf_lo(unsigned u) { return __uint_as_float(u << 16); }
; #define tid (otid())
; __global__ void __launch_bounds__(512, 2) mega_fwd(Args a) {
;     ...
;         const int r32 = lane & 31, hi = lane >> 5, iblk = wave >> 1, dblk = wave & 1;
;         const int jt = tid >> 2, qd = tid & 3;
;         u32x4 r0, r1; f32x4 lgv[4], lbv[4];
;         const int ustep = (G == 256) ? 1 : G;
;         const int jx = vcu & 31;
;         const int u0 = (G == 256) ? (256 * (vcu >> 5) + (jx < 16 ? 7 * jx : 112 + 9 * (jx - 16))) : vcu;
;         const int ucnt = (G == 256) ? (bx < 128 ? 7 : 9) : (vcu < 2048 ? (2047 - vcu) / G + 1 : 0);
;         if (ucnt > 0) { const bf16_t* vp = Z + ((size_t)(u0 >> 3) * 128 + jt) * NZ + 1024 + (u0 & 7) * 64 + 16 * qd; r0 = *(const u32x4*)vp; r1 = *(const u32x4*)(vp + 8);
; #pragma unroll
;             for (int e4 = 0; e4 < 4; ++e4) { lgv[e4] = *(const f32x4*)(KA->gm_ln_g + (u0 & 7) * 64 + 16 * qd + 4 * e4); lbv[e4] = *(const f32x4*)(KA->gm_ln_b + (u0 & 7) * 64 + 16 * qd + 4 * e4); } }
;         for (int ui = 0, u = u0; ui < ucnt; ++ui, u += ustep) {
;             const int blk = u >> 3, h = u & 7; const size_t t0 = (size_t)blk * 128;
;             {
;                 float xv[16];
;                 xv[0] = bf_lo(r0.x); xv[1] = bf_hi(r0.x); xv[2] = bf_lo(r0.y); xv[3] = bf_hi(r0.y); xv[4] = bf_lo(r0.z); xv[5] = bf_hi(r0.z); xv[6] = bf_lo(r0.w); xv[7] = bf_hi(r0.w);
;                 xv[8] = bf_lo(r1.x); xv[9] = bf_hi(r1.x); xv[10] = bf_lo(r1.y); xv[11] = bf_hi(r1.y); xv[12] = bf_lo(r1.z); xv[13] = bf_hi(r1.z); xv[14] = bf_lo(r1.w); xv[15] = bf_hi(r1.w);
;                 float sm = 0.f;
; #pragma unroll
;                 for (int e = 0; e < 16; ++e) sm += xv[e];
;                 sm += __shfl_xor(sm, 1); sm += __shfl_xor(sm, 2);
;                 const float mu = sm * (1.0f / 64.0f); float q = 0.f;
; #pragma unroll
;                 for (int e = 0; e < 16; ++e) { xv[e] -= mu; q += xv[e] * xv[e]; }
;                 q += __shfl_xor(q, 1); q += __shfl_xor(q, 2);
;                 const float rstd = rsqrtf(q * (1.0f / 64.0f) + EPS);
; #pragma unroll
;                 for (int e = 0; e < 16; ++e) { const float y = xv[e] * rstd * lgv[e >> 2][e & 3] + lbv[e >> 2][e & 3]; VLT[(16 * qd + e) * VLP + jt] = (bf16_t)(pk2(y, 0.f) & 0xffffu); }
;             }
;             const int un = u + ustep;
.LBB0_340:
	s_cmp_lt_i32 s18, 1
	s_cbranch_scc1 .LBB0_361
	s_load_dwordx2 s[8:9], s[6:7], 0xb8
	s_load_dwordx4 s[40:43], s[6:7], 0x58
	s_load_dwordx2 s[16:17], s[6:7], 0x70
	s_and_b64 s[4:5], s[4:5], exec
	s_cselect_b32 s19, 1, s28
	s_mov_b32 s38, 0xffff0000
	v_mov_b32_e32 v111, 0x358637bd
	v_and_b32_e32 v104, 3, v0
	v_lshrrev_b32_e32 v105, 2, v0
	v_and_b32_e32 v106, 31, v0
	v_bfe_u32 v107, v0, 5, 1
	s_lshr_b32 s4, s20, 7
	s_bfe_u32 s5, s20, 0x10006
	s_lshl_b32 s10, s4, 5
	v_or_b32_e32 v108, s10, v106
	v_mul_u32_u24_e32 v112, 0xc00, v105
	v_lshl_add_u32 v112, v104, 5, v112
	v_add_u32_e32 v112, 0x800, v112
	s_lshl_b32 s11, s5, 6
	s_add_u32 s11, s11, 0x400
	v_mul_u32_u24_e32 v113, 0xc00, v108
	v_lshl_add_u32 v113, v107, 3, v113
	v_add_u32_e32 v113, s11, v113
	v_lshlrev_b32_e32 v116, 11, v108
	v_lshl_add_u32 v116, v107, 3, v116
	v_add_u32_e32 v116, s11, v116
	v_lshlrev_b32_e32 v114, 8, v108
	v_lshl_add_u32 v114, v107, 4, v114
	v_lshlrev_b32_e32 v115, 2, v108
	v_mul_u32_u24_e32 v117, 0x1100, v104
	v_lshl_add_u32 v117, v105, 1, v117
	s_lshl_b32 s12, s5, 5
	v_or_b32_e32 v118, s12, v106
	v_mul_u32_u24_e32 v118, 0x110, v118
	v_lshl_add_u32 v118, v107, 4, v118
	v_lshlrev_b32_e32 v119, 6, v104
	v_add_u32_e32 v119, 0x8800, v119
	s_waitcnt lgkmcnt(0)
	s_cmp_ge_u32 s20, 0x100
	s_cbranch_scc1 .Lp3_notab
	s_cmp_lt_u32 s20, 0x80
	s_cselect_b32 s22, s40, s42
	s_cselect_b32 s23, s41, s43
	v_and_b32_e32 v109, 0x7f, v0
	v_lshlrev_b32_e32 v109, 4, v109
	global_load_dwordx4 v[216:219], v109, s[22:23]
	v_lshlrev_b32_e32 v110, 4, v0
	v_add_u32_e32 v110, 0x8800, v110
	s_waitcnt vmcnt(0)
	ds_write_b128 v110, v[216:219]
.Lp3_notab:
	s_mov_b32 s45, 0
	s_lshr_b32 s21, s39, 3
	s_and_b32 s22, s39, 7
	s_mul_i32 s24, s21, 0x60000
	s_lshl_b32 s25, s22, 7
	s_add_u32 s24, s24, s25
	s_add_u32 s24, s24, 0x6000000
	s_add_u32 s26, s8, s24
	s_addc_u32 s27, s9, 0
	s_lshl_b32 s24, s22, 15
	s_add_u32 s24, s24, 0x180000
	s_add_u32 s36, s8, s24
	s_addc_u32 s37, s9, 0
	s_lshl_b32 s24, s22, 9
	s_add_u32 s46, s16, s24
	s_addc_u32 s47, s17, 0
	global_load_dwordx4 v[16:19], v112, s[26:27]
	global_load_dwordx4 v[20:23], v112, s[26:27] offset:16
	global_load_dwordx4 v[40:43], v114, s[36:37]
	global_load_dwordx4 v[44:47], v114, s[36:37] offset:32
	global_load_dwordx4 v[48:51], v114, s[36:37] offset:64
	global_load_dwordx4 v[52:55], v114, s[36:37] offset:96
	global_load_dwordx4 v[56:59], v114, s[36:37] offset:128
	global_load_dwordx4 v[60:63], v114, s[36:37] offset:160
	global_load_dwordx4 v[64:67], v114, s[36:37] offset:192
	global_load_dwordx4 v[68:71], v114, s[36:37] offset:224
	global_load_dwordx2 v[24:25], v113, s[26:27]
	global_load_dwordx2 v[26:27], v113, s[26:27] offset:16
	global_load_dwordx2 v[28:29], v113, s[26:27] offset:32
	global_load_dwordx2 v[30:31], v113, s[26:27] offset:48
	global_load_dword v32, v115, s[46:47]
	s_waitcnt lgkmcnt(0)
	s_barrier
.Lp3_body0:
	s_add_u32 s44, s45, 1
	s_cmp_lt_u32 s44, s18
	s_cbranch_scc0 .Lp3_last0
	s_add_u32 s44, s39, s19
	s_lshr_b32 s21, s44, 3
	s_and_b32 s22, s44, 7
	s_mul_i32 s24, s21, 0x60000
	s_lshl_b32 s25, s22, 7
	s_add_u32 s24, s24, s25
	s_add_u32 s24, s24, 0x6000000
	s_add_u32 s26, s8, s24
	s_addc_u32 s27, s9, 0
	s_lshl_b32 s24, s22, 15
	s_add_u32 s24, s24, 0x180000
	s_add_u32 s36, s8, s24
	s_addc_u32 s37, s9, 0
	s_lshl_b32 s24, s22, 9
	s_add_u32 s46, s16, s24
	s_addc_u32 s47, s17, 0
	global_load_dwordx4 v[72:75], v112, s[26:27]
	global_load_dwordx4 v[76:79], v112, s[26:27] offset:16
	global_load_dwordx4 v[120:123], v114, s[36:37]
	global_load_dwordx4 v[124:127], v114, s[36:37] offset:32
	global_load_dwordx4 v[128:131], v114, s[36:37] offset:64
	global_load_dwordx4 v[132:135], v114, s[36:37] offset:96
	global_load_dwordx4 v[136:139], v114, s[36:37] offset:128
	global_load_dwordx4 v[140:143], v114, s[36:37] offset:160
	global_load_dwordx4 v[144:147], v114, s[36:37] offset:192
	global_load_dwordx4 v[148:151], v114, s[36:37] offset:224
	global_load_dwordx2 v[80:81], v113, s[26:27]
	global_load_dwordx2 v[82:83], v113, s[26:27] offset:16
	global_load_dwordx2 v[84:85], v113, s[26:27] offset:32
	global_load_dwordx2 v[86:87], v113, s[26:27] offset:48
	global_load_dword v34, v115, s[46:47]
	s_and_b32 s22, s39, 7
	s_lshl_b32 s22, s22, 8
	v_add_u32_e32 v232, s22, v119
	ds_read_b128 v[152:155], v232
	ds_read_b128 v[156:159], v232 offset:16
	ds_read_b128 v[160:163], v232 offset:32
	ds_read_b128 v[164:167], v232 offset:48
	ds_read_b128 v[168:171], v232 offset:2048
	ds_read_b128 v[172:175], v232 offset:2064
	ds_read_b128 v[176:179], v232 offset:2080
	ds_read_b128 v[180:183], v232 offset:2096
	s_waitcnt vmcnt(29)
	v_lshlrev_b32_e32 v200, 16, v16
	v_and_b32_e32 v201, s38, v16
	v_lshlrev_b32_e32 v202, 16, v17
	v_and_b32_e32 v203, s38, v17
	v_lshlrev_b32_e32 v204, 16, v18
	v_and_b32_e32 v205, s38, v18
	v_lshlrev_b32_e32 v206, 16, v19
	v_and_b32_e32 v207, s38, v19
	s_waitcnt vmcnt(28)
; #define LAS __attribute__((address_space(3)))
; __device__ __forceinline__ unsigned pk2(float lo, float hi) { f32x2_t v = {lo, hi}; bf16x2_t b = __builtin_convertvector(v, bf16x2_t); return __builtin_bit_cast(unsigned, b); }
; __device__ __forceinline__ float bf_lo(unsigned u) { return __uint_as_float(u << 16); }
; __device__ __forceinline__ float bf_hi(unsigned u) { return __uint_as_float(u & 0xffff0000u); }
; __global__ void __launch_bounds__(512, 2) mega_fwd(Args a) {
;     ...
;                 float xv[16];
;                 xv[0] = bf_lo(r0.x); xv[1] = bf_hi(r0.x); xv[2] = bf_lo(r0.y); xv[3] = bf_hi(r0.y); xv[4] = bf_lo(r0.z); xv[5] = bf_hi(r0.z); xv[6] = bf_lo(r0.w); xv[7] = bf_hi(r0.w);
;                 xv[8] = bf_lo(r1.x); xv[9] = bf_hi(r1.x); xv[10] = bf_lo(r1.y); xv[11] = bf_hi(r1.y); xv[12] = bf_lo(r1.z); xv[13] = bf_hi(r1.z); xv[14] = bf_lo(r1.w); xv[15] = bf_hi(r1.w);
;                 float sm = 0.f;
; #pragma unroll
;                 for (int e = 0; e < 16; ++e) sm += xv[e];
;                 sm += __shfl_xor(sm, 1); sm += __shfl_xor(sm, 2);
;                 const float mu = sm * (1.0f / 64.0f); float q = 0.f;
; #pragma unroll
;                 for (int e = 0; e < 16; ++e) { xv[e] -= mu; q += xv[e] * xv[e]; }
;                 q += __shfl_xor(q, 1); q += __shfl_xor(q, 2);
;                 const float rstd = rsqrtf(q * (1.0f / 64.0f) + EPS);
; #pragma unroll
;                 for (int e = 0; e < 16; ++e) { const float y = xv[e] * rstd * lgv[e >> 2][e & 3] + lbv[e >> 2][e & 3]; VLT[(16 * qd + e) * VLP + jt] = (bf16_t)(pk2(y, 0.f) & 0xffffu); }
;     ...
;             __syncthreads();
;             {
;                 f32x16 acc;
; #pragma unroll
;                 for (int r = 0; r < 16; ++r) acc[r] = 0.f;
;                 const LAS bf16_t* vl = VLT + (32 * dblk + r32) * VLP + 8 * hi;
; #pragma unroll
;                 for (int s = 0; s < 8; ++s) if (s < 4 || iblk >= 2) {
;                     const bf16x8 vf = *(const LAS bf16x8*)(vl + 16 * s);
;                     acc = __builtin_amdgcn_mfma_f32_32x32x16_bf16(vf, wf[s], acc, 0, 0, 0);
;                 }
	v_lshlrev_b32_e32 v208, 16, v20
	v_and_b32_e32 v209, s38, v20
	v_lshlrev_b32_e32 v210, 16, v21
	v_and_b32_e32 v211, s38, v21
	v_lshlrev_b32_e32 v212, 16, v22
	v_and_b32_e32 v213, s38, v22
	v_lshlrev_b32_e32 v214, 16, v23
	v_and_b32_e32 v215, s38, v23
	v_pk_add_f32 v[216:217], v[200:201], v[202:203]
	v_pk_add_f32 v[218:219], v[204:205], v[206:207]
	v_pk_add_f32 v[220:221], v[208:209], v[210:211]
	v_pk_add_f32 v[222:223], v[212:213], v[214:215]
	v_pk_add_f32 v[216:217], v[216:217], v[218:219]
	v_pk_add_f32 v[220:221], v[220:221], v[222:223]
	v_pk_add_f32 v[216:217], v[216:217], v[220:221]
	v_add_f32_e32 v216, v216, v217
	s_nop 1
	v_add_f32_dpp v217, v216, v216 quad_perm:[1,0,3,2] row_mask:0xf bank_mask:0xf
	s_nop 1
	v_add_f32_dpp v216, v217, v217 quad_perm:[2,3,0,1] row_mask:0xf bank_mask:0xf
	v_mul_f32_e32 v216, 0xbc800000, v216
	v_pk_add_f32 v[200:201], v[200:201], v[216:217] op_sel_hi:[1,0]
	v_pk_add_f32 v[202:203], v[202:203], v[216:217] op_sel_hi:[1,0]
	v_pk_add_f32 v[204:205], v[204:205], v[216:217] op_sel_hi:[1,0]
	v_pk_add_f32 v[206:207], v[206:207], v[216:217] op_sel_hi:[1,0]
	v_pk_add_f32 v[208:209], v[208:209], v[216:217] op_sel_hi:[1,0]
	v_pk_add_f32 v[210:211], v[210:211], v[216:217] op_sel_hi:[1,0]
	v_pk_add_f32 v[212:213], v[212:213], v[216:217] op_sel_hi:[1,0]
	v_pk_add_f32 v[214:215], v[214:215], v[216:217] op_sel_hi:[1,0]
	v_pk_mul_f32 v[218:219], v[200:201], v[200:201]
	v_pk_mul_f32 v[220:221], v[202:203], v[202:203]
	v_pk_fma_f32 v[218:219], v[204:205], v[204:205], v[218:219]
	v_pk_fma_f32 v[220:221], v[206:207], v[206:207], v[220:221]
	v_pk_fma_f32 v[218:219], v[208:209], v[208:209], v[218:219]
	v_pk_fma_f32 v[220:221], v[210:211], v[210:211], v[220:221]
	v_pk_fma_f32 v[218:219], v[212:213], v[212:213], v[218:219]
	v_pk_fma_f32 v[220:221], v[214:215], v[214:215], v[220:221]
	v_pk_add_f32 v[218:219], v[218:219], v[220:221]
	v_add_f32_e32 v218, v218, v219
	s_nop 1
	v_add_f32_dpp v219, v218, v218 quad_perm:[1,0,3,2] row_mask:0xf bank_mask:0xf
	s_nop 1
	v_add_f32_dpp v218, v219, v219 quad_perm:[2,3,0,1] row_mask:0xf bank_mask:0xf
	v_fmamk_f32 v218, v218, 0x3c800000, v111
	v_rsq_f32_e32 v218, v218
	s_nop 0
	v_pk_mul_f32 v[200:201], v[200:201], v[218:219] op_sel_hi:[1,0]
	v_pk_mul_f32 v[202:203], v[202:203], v[218:219] op_sel_hi:[1,0]
	v_pk_mul_f32 v[204:205], v[204:205], v[218:219] op_sel_hi:[1,0]
	v_pk_mul_f32 v[206:207], v[206:207], v[218:219] op_sel_hi:[1,0]
	v_pk_mul_f32 v[208:209], v[208:209], v[218:219] op_sel_hi:[1,0]
	v_pk_mul_f32 v[210:211], v[210:211], v[218:219] op_sel_hi:[1,0]
	v_pk_mul_f32 v[212:213], v[212:213], v[218:219] op_sel_hi:[1,0]
	v_pk_mul_f32 v[214:215], v[214:215], v[218:219] op_sel_hi:[1,0]
	s_waitcnt lgkmcnt(0)
	v_pk_fma_f32 v[200:201], v[200:201], v[152:153], v[168:169]
	v_pk_fma_f32 v[202:203], v[202:203], v[154:155], v[170:171]
	v_pk_fma_f32 v[204:205], v[204:205], v[156:157], v[172:173]
	v_pk_fma_f32 v[206:207], v[206:207], v[158:159], v[174:175]
	v_pk_fma_f32 v[208:209], v[208:209], v[160:161], v[176:177]
	v_pk_fma_f32 v[210:211], v[210:211], v[162:163], v[178:179]
	v_pk_fma_f32 v[212:213], v[212:213], v[164:165], v[180:181]
	v_pk_fma_f32 v[214:215], v[214:215], v[166:167], v[182:183]
	v_cvt_pk_bf16_f32 v224, v200, v201
	v_cvt_pk_bf16_f32 v225, v202, v203
	v_cvt_pk_bf16_f32 v226, v204, v205
	v_cvt_pk_bf16_f32 v227, v206, v207
	v_cvt_pk_bf16_f32 v228, v208, v209
	v_cvt_pk_bf16_f32 v229, v210, v211
	v_cvt_pk_bf16_f32 v230, v212, v213
	v_cvt_pk_bf16_f32 v231, v214, v215
	ds_write_b16 v117, v224 offset:0
	ds_write_b16_d16_hi v117, v224 offset:272
	ds_write_b16 v117, v225 offset:544
	ds_write_b16_d16_hi v117, v225 offset:816
	ds_write_b16 v117, v226 offset:1088
	ds_write_b16_d16_hi v117, v226 offset:1360
	ds_write_b16 v117, v227 offset:1632
	ds_write_b16_d16_hi v117, v227 offset:1904
	ds_write_b16 v117, v228 offset:2176
	ds_write_b16_d16_hi v117, v228 offset:2448
	ds_write_b16 v117, v229 offset:2720
	ds_write_b16_d16_hi v117, v229 offset:2992
	ds_write_b16 v117, v230 offset:3264
	ds_write_b16_d16_hi v117, v230 offset:3536
	ds_write_b16 v117, v231 offset:3808
	ds_write_b16_d16_hi v117, v231 offset:4080
	s_waitcnt lgkmcnt(0)
	s_barrier
	ds_read_b128 v[88:91], v118 offset:0
	ds_read_b128 v[92:95], v118 offset:32
	ds_read_b128 v[96:99], v118 offset:64
	ds_read_b128 v[100:103], v118 offset:96
	s_waitcnt vmcnt(24) lgkmcnt(3)
	v_mfma_f32_32x32x16_bf16 v[0:15], v[88:91], v[40:43], 0
	s_waitcnt lgkmcnt(2)
	v_mfma_f32_32x32x16_bf16 v[0:15], v[92:95], v[44:47], v[0:15]
	s_waitcnt lgkmcnt(1)
	v_mfma_f32_32x32x16_bf16 v[0:15], v[96:99], v[48:51], v[0:15]
	s_waitcnt lgkmcnt(0)
	v_mfma_f32_32x32x16_bf16 v[0:15], v[100:103], v[52:55], v[0:15]
	s_cmp_lt_u32 s20, 0x100
	s_cbranch_scc1 .Lp3_half0
	ds_read_b128 v[88:91], v118 offset:128
	ds_read_b128 v[92:95], v118 offset:160
	ds_read_b128 v[96:99], v118 offset:192
	ds_read_b128 v[100:103], v118 offset:224
	s_waitcnt vmcnt(20)
	s_waitcnt lgkmcnt(3)
	v_mfma_f32_32x32x16_bf16 v[0:15], v[88:91], v[56:59], v[0:15]
	s_waitcnt lgkmcnt(2)
	v_mfma_f32_32x32x16_bf16 v[0:15], v[92:95], v[60:63], v[0:15]
	s_waitcnt lgkmcnt(1)
	v_mfma_f32_32x32x16_bf16 v[0:15], v[96:99], v[64:67], v[0:15]
	s_waitcnt lgkmcnt(0)
	v_mfma_f32_32x32x16_bf16 v[0:15], v[100:103], v[68:71], v[0:15]
; __device__ __forceinline__ unsigned pk2(float lo, float hi) { f32x2_t v = {lo, hi}; bf16x2_t b = __builtin_convertvector(v, bf16x2_t); return __builtin_bit_cast(unsigned, b); }
; __device__ __forceinline__ float bf_lo(unsigned u) { return __uint_as_float(u << 16); }
; __device__ __forceinline__ float bf_hi(unsigned u) { return __uint_as_float(u & 0xffff0000u); }
; __global__ void __launch_bounds__(512, 2) mega_fwd(Args a) {
;     ...
;         for (int ui = 0, u = u0; ui < ucnt; ++ui, u += ustep) {
;             const int blk = u >> 3, h = u & 7; const size_t t0 = (size_t)blk * 128;
;             {
;                 float xv[16];
;                 xv[0] = bf_lo(r0.x); xv[1] = bf_hi(r0.x); xv[2] = bf_lo(r0.y); xv[3] = bf_hi(r0.y); xv[4] = bf_lo(r0.z); xv[5] = bf_hi(r0.z); xv[6] = bf_lo(r0.w); xv[7] = bf_hi(r0.w);
;                 xv[8] = bf_lo(r1.x); xv[9] = bf_hi(r1.x); xv[10] = bf_lo(r1.y); xv[11] = bf_hi(r1.y); xv[12] = bf_lo(r1.z); xv[13] = bf_hi(r1.z); xv[14] = bf_lo(r1.w); xv[15] = bf_hi(r1.w);
;                 float sm = 0.f;
; #pragma unroll
;                 for (int e = 0; e < 16; ++e) sm += xv[e];
;                 sm += __shfl_xor(sm, 1); sm += __shfl_xor(sm, 2);
;                 const float mu = sm * (1.0f / 64.0f); float q = 0.f;
; #pragma unroll
;                 for (int e = 0; e < 16; ++e) { xv[e] -= mu; q += xv[e] * xv[e]; }
;                 q += __shfl_xor(q, 1); q += __shfl_xor(q, 2);
;                 const float rstd = rsqrtf(q * (1.0f / 64.0f) + EPS);
; #pragma unroll
;                 for (int e = 0; e < 16; ++e) { const float y = xv[e] * rstd * lgv[e >> 2][e & 3] + lbv[e >> 2][e & 3]; VLT[(16 * qd + e) * VLP + jt] = (bf16_t)(pk2(y, 0.f) & 0xffffu); }
;     ...
;                 bf16_t* op = AO + (t0 + itok) * DM + 512 + h * 64 + 32 * dblk + 4 * hi;
; #pragma unroll
;                 for (int g = 0; g < 4; ++g) {
;                     u32x2 w; w.x = pk2(bf_lo(uu[g].x) * (acc[4 * g] + bsp), bf_hi(uu[g].x) * (acc[4 * g + 1] + bsp)); w.y = pk2(bf_lo(uu[g].y) * (acc[4 * g + 2] + bsp), bf_hi(uu[g].y) * (acc[4 * g + 3] + bsp));
;                     *(u32x2*)(op + 8 * g) = w;
;                 }
;             }
;             __syncthreads();
.Lp3_half0:
	s_lshr_b32 s21, s39, 3
	s_and_b32 s22, s39, 7
	s_lshl_b32 s24, s21, 18
	s_lshl_b32 s25, s22, 7
	s_add_u32 s24, s24, s25
	s_add_u32 s24, s24, 0x14a00000
	s_add_u32 s48, s8, s24
	s_addc_u32 s49, s9, 0
	s_waitcnt vmcnt(15)
	v_lshlrev_b32_e32 v200, 16, v24
	v_and_b32_e32 v201, s38, v24
	v_lshlrev_b32_e32 v202, 16, v25
	v_and_b32_e32 v203, s38, v25
	v_lshlrev_b32_e32 v204, 16, v26
	v_and_b32_e32 v205, s38, v26
	v_lshlrev_b32_e32 v206, 16, v27
	v_and_b32_e32 v207, s38, v27
	v_lshlrev_b32_e32 v208, 16, v28
	v_and_b32_e32 v209, s38, v28
	v_lshlrev_b32_e32 v210, 16, v29
	v_and_b32_e32 v211, s38, v29
	v_lshlrev_b32_e32 v212, 16, v30
	v_and_b32_e32 v213, s38, v30
	v_lshlrev_b32_e32 v214, 16, v31
	v_and_b32_e32 v215, s38, v31
	s_nop 7
	v_pk_add_f32 v[0:1], v[0:1], v[32:33] op_sel_hi:[1,0]
	v_pk_add_f32 v[2:3], v[2:3], v[32:33] op_sel_hi:[1,0]
	v_pk_add_f32 v[4:5], v[4:5], v[32:33] op_sel_hi:[1,0]
	v_pk_add_f32 v[6:7], v[6:7], v[32:33] op_sel_hi:[1,0]
	v_pk_add_f32 v[8:9], v[8:9], v[32:33] op_sel_hi:[1,0]
	v_pk_add_f32 v[10:11], v[10:11], v[32:33] op_sel_hi:[1,0]
	v_pk_add_f32 v[12:13], v[12:13], v[32:33] op_sel_hi:[1,0]
	v_pk_add_f32 v[14:15], v[14:15], v[32:33] op_sel_hi:[1,0]
	v_pk_mul_f32 v[0:1], v[0:1], v[200:201]
	v_pk_mul_f32 v[2:3], v[2:3], v[202:203]
	v_pk_mul_f32 v[4:5], v[4:5], v[204:205]
	v_pk_mul_f32 v[6:7], v[6:7], v[206:207]
	v_pk_mul_f32 v[8:9], v[8:9], v[208:209]
	v_pk_mul_f32 v[10:11], v[10:11], v[210:211]
	v_pk_mul_f32 v[12:13], v[12:13], v[212:213]
	v_pk_mul_f32 v[14:15], v[14:15], v[214:215]
	v_cvt_pk_bf16_f32 v224, v0, v1
	v_cvt_pk_bf16_f32 v225, v2, v3
	v_cvt_pk_bf16_f32 v226, v4, v5
	v_cvt_pk_bf16_f32 v227, v6, v7
	v_cvt_pk_bf16_f32 v228, v8, v9
	v_cvt_pk_bf16_f32 v229, v10, v11
	v_cvt_pk_bf16_f32 v230, v12, v13
	v_cvt_pk_bf16_f32 v231, v14, v15
	global_store_dwordx2 v116, v[224:225], s[48:49]
	global_store_dwordx2 v116, v[226:227], s[48:49] offset:16
	global_store_dwordx2 v116, v[228:229], s[48:49] offset:32
	global_store_dwordx2 v116, v[230:231], s[48:49] offset:48
	s_add_u32 s45, s45, 1
	s_add_u32 s39, s39, s19
.Lp3_body1:
	s_add_u32 s44, s45, 1
	s_cmp_lt_u32 s44, s18
	s_cbranch_scc0 .Lp3_last1
	s_add_u32 s44, s39, s19
	s_lshr_b32 s21, s44, 3
	s_and_b32 s22, s44, 7
	s_mul_i32 s24, s21, 0x60000
	s_lshl_b32 s25, s22, 7
	s_add_u32 s24, s24, s25
	s_add_u32 s24, s24, 0x6000000
	s_add_u32 s26, s8, s24
	s_addc_u32 s27, s9, 0
	s_lshl_b32 s24, s22, 15
	s_add_u32 s24, s24, 0x180000
	s_add_u32 s36, s8, s24
	s_addc_u32 s37, s9, 0
	s_lshl_b32 s24, s22, 9
	s_add_u32 s46, s16, s24
	s_addc_u32 s47, s17, 0
	global_load_dwordx4 v[16:19], v112, s[26:27]
	global_load_dwordx4 v[20:23], v112, s[26:27] offset:16
	global_load_dwordx4 v[40:43], v114, s[36:37]
	global_load_dwordx4 v[44:47], v114, s[36:37] offset:32
	global_load_dwordx4 v[48:51], v114, s[36:37] offset:64
	global_load_dwordx4 v[52:55], v114, s[36:37] offset:96
	global_load_dwordx4 v[56:59], v114, s[36:37] offset:128
	global_load_dwordx4 v[60:63], v114, s[36:37] offset:160
	global_load_dwordx4 v[64:67], v114, s[36:37] offset:192
	global_load_dwordx4 v[68:71], v114, s[36:37] offset:224
	global_load_dwordx2 v[24:25], v113, s[26:27]
	global_load_dwordx2 v[26:27], v113, s[26:27] offset:16
	global_load_dwordx2 v[28:29], v113, s[26:27] offset:32
	global_load_dwordx2 v[30:31], v113, s[26:27] offset:48
	global_load_dword v32, v115, s[46:47]
	s_and_b32 s22, s39, 7
	s_lshl_b32 s22, s22, 8
	v_add_u32_e32 v232, s22, v119
	ds_read_b128 v[152:155], v232
	ds_read_b128 v[156:159], v232 offset:16
	ds_read_b128 v[160:163], v232 offset:32
	ds_read_b128 v[164:167], v232 offset:48
	ds_read_b128 v[168:171], v232 offset:2048
	ds_read_b128 v[172:175], v232 offset:2064
	ds_read_b128 v[176:179], v232 offset:2080
	ds_read_b128 v[180:183], v232 offset:2096
	s_waitcnt vmcnt(29)
	v_lshlrev_b32_e32 v200, 16, v72
	v_and_b32_e32 v201, s38, v72
	v_lshlrev_b32_e32 v202, 16, v73
	v_and_b32_e32 v203, s38, v73
	v_lshlrev_b32_e32 v204, 16, v74
	v_and_b32_e32 v205, s38, v74
	v_lshlrev_b32_e32 v206, 16, v75
	v_and_b32_e32 v207, s38, v75
	s_waitcnt vmcnt(28)
	v_lshlrev_b32_e32 v208, 16, v76
	v_and_b32_e32 v209, s38, v76
	v_lshlrev_b32_e32 v210, 16, v77
	v_and_b32_e32 v211, s38, v77
	v_lshlrev_b32_e32 v212, 16, v78
	v_and_b32_e32 v213, s38, v78
	v_lshlrev_b32_e32 v214, 16, v79
	v_and_b32_e32 v215, s38, v79
	v_pk_add_f32 v[216:217], v[200:201], v[202:203]
	v_pk_add_f32 v[218:219], v[204:205], v[206:207]
	v_pk_add_f32 v[220:221], v[208:209], v[210:211]
	v_pk_add_f32 v[222:223], v[212:213], v[214:215]
	v_pk_add_f32 v[216:217], v[216:217], v[218:219]
	v_pk_add_f32 v[220:221], v[220:221], v[222:223]
	v_pk_add_f32 v[216:217], v[216:217], v[220:221]
	v_add_f32_e32 v216, v216, v217
	s_nop 1
	v_add_f32_dpp v217, v216, v216 quad_perm:[1,0,3,2] row_mask:0xf bank_mask:0xf
	s_nop 1
	v_add_f32_dpp v216, v217, v217 quad_perm:[2,3,0,1] row_mask:0xf bank_mask:0xf
	v_mul_f32_e32 v216, 0xbc800000, v216
	v_pk_add_f32 v[200:201], v[200:201], v[216:217] op_sel_hi:[1,0]
	v_pk_add_f32 v[202:203], v[202:203], v[216:217] op_sel_hi:[1,0]
	v_pk_add_f32 v[204:205], v[204:205], v[216:217] op_sel_hi:[1,0]
	v_pk_add_f32 v[206:207], v[206:207], v[216:217] op_sel_hi:[1,0]
	v_pk_add_f32 v[208:209], v[208:209], v[216:217] op_sel_hi:[1,0]
	v_pk_add_f32 v[210:211], v[210:211], v[216:217] op_sel_hi:[1,0]
	v_pk_add_f32 v[212:213], v[212:213], v[216:217] op_sel_hi:[1,0]
	v_pk_add_f32 v[214:215], v[214:215], v[216:217] op_sel_hi:[1,0]
	v_pk_mul_f32 v[218:219], v[200:201], v[200:201]
	v_pk_mul_f32 v[220:221], v[202:203], v[202:203]
	v_pk_fma_f32 v[218:219], v[204:205], v[204:205], v[218:219]
	v_pk_fma_f32 v[220:221], v[206:207], v[206:207], v[220:221]
	v_pk_fma_f32 v[218:219], v[208:209], v[208:209], v[218:219]
	v_pk_fma_f32 v[220:221], v[210:211], v[210:211], v[220:221]
	v_pk_fma_f32 v[218:219], v[212:213], v[212:213], v[218:219]
	v_pk_fma_f32 v[220:221], v[214:215], v[214:215], v[220:221]
	v_pk_add_f32 v[218:219], v[218:219], v[220:221]
	v_add_f32_e32 v218, v218, v219
	s_nop 1
	v_add_f32_dpp v219, v218, v218 quad_perm:[1,0,3,2] row_mask:0xf bank_mask:0xf
	s_nop 1
	v_add_f32_dpp v218, v219, v219 quad_perm:[2,3,0,1] row_mask:0xf bank_mask:0xf
	v_fmamk_f32 v218, v218, 0x3c800000, v111
	v_rsq_f32_e32 v218, v218
	s_nop 0
	v_pk_mul_f32 v[200:201], v[200:201], v[218:219] op_sel_hi:[1,0]
	v_pk_mul_f32 v[202:203], v[202:203], v[218:219] op_sel_hi:[1,0]
	v_pk_mul_f32 v[204:205], v[204:205], v[218:219] op_sel_hi:[1,0]
	v_pk_mul_f32 v[206:207], v[206:207], v[218:219] op_sel_hi:[1,0]
	v_pk_mul_f32 v[208:209], v[208:209], v[218:219] op_sel_hi:[1,0]
	v_pk_mul_f32 v[210:211], v[210:211], v[218:219] op_sel_hi:[1,0]
	v_pk_mul_f32 v[212:213], v[212:213], v[218:219] op_sel_hi:[1,0]
	v_pk_mul_f32 v[214:215], v[214:215], v[218:219] op_sel_hi:[1,0]
	s_waitcnt lgkmcnt(0)
; #define LAS __attribute__((address_space(3)))
; __device__ __forceinline__ unsigned pk2(float lo, float hi) { f32x2_t v = {lo, hi}; bf16x2_t b = __builtin_convertvector(v, bf16x2_t); return __builtin_bit_cast(unsigned, b); }
; __device__ __forceinline__ float bf_lo(unsigned u) { return __uint_as_float(u << 16); }
; __device__ __forceinline__ float bf_hi(unsigned u) { return __uint_as_float(u & 0xffff0000u); }
; __global__ void __launch_bounds__(512, 2) mega_fwd(Args a) {
;     ...
;             __syncthreads();
;             {
;                 f32x16 acc;
; #pragma unroll
;                 for (int r = 0; r < 16; ++r) acc[r] = 0.f;
;                 const LAS bf16_t* vl = VLT + (32 * dblk + r32) * VLP + 8 * hi;
; #pragma unroll
;                 for (int s = 0; s < 8; ++s) if (s < 4 || iblk >= 2) {
;                     const bf16x8 vf = *(const LAS bf16x8*)(vl + 16 * s);
;                     acc = __builtin_amdgcn_mfma_f32_32x32x16_bf16(vf, wf[s], acc, 0, 0, 0);
;                 }
;                 bf16_t* op = AO + (t0 + itok) * DM + 512 + h * 64 + 32 * dblk + 4 * hi;
; #pragma unroll
;                 for (int g = 0; g < 4; ++g) {
;                     u32x2 w; w.x = pk2(bf_lo(uu[g].x) * (acc[4 * g] + bsp), bf_hi(uu[g].x) * (acc[4 * g + 1] + bsp)); w.y = pk2(bf_lo(uu[g].y) * (acc[4 * g + 2] + bsp), bf_hi(uu[g].y) * (acc[4 * g + 3] + bsp));
;                     *(u32x2*)(op + 8 * g) = w;
;                 }
	v_pk_fma_f32 v[200:201], v[200:201], v[152:153], v[168:169]
	v_pk_fma_f32 v[202:203], v[202:203], v[154:155], v[170:171]
	v_pk_fma_f32 v[204:205], v[204:205], v[156:157], v[172:173]
	v_pk_fma_f32 v[206:207], v[206:207], v[158:159], v[174:175]
	v_pk_fma_f32 v[208:209], v[208:209], v[160:161], v[176:177]
	v_pk_fma_f32 v[210:211], v[210:211], v[162:163], v[178:179]
	v_pk_fma_f32 v[212:213], v[212:213], v[164:165], v[180:181]
	v_pk_fma_f32 v[214:215], v[214:215], v[166:167], v[182:183]
	v_cvt_pk_bf16_f32 v224, v200, v201
	v_cvt_pk_bf16_f32 v225, v202, v203
	v_cvt_pk_bf16_f32 v226, v204, v205
	v_cvt_pk_bf16_f32 v227, v206, v207
	v_cvt_pk_bf16_f32 v228, v208, v209
	v_cvt_pk_bf16_f32 v229, v210, v211
	v_cvt_pk_bf16_f32 v230, v212, v213
	v_cvt_pk_bf16_f32 v231, v214, v215
	ds_write_b16 v117, v224 offset:17408
	ds_write_b16_d16_hi v117, v224 offset:17680
	ds_write_b16 v117, v225 offset:17952
	ds_write_b16_d16_hi v117, v225 offset:18224
	ds_write_b16 v117, v226 offset:18496
	ds_write_b16_d16_hi v117, v226 offset:18768
	ds_write_b16 v117, v227 offset:19040
	ds_write_b16_d16_hi v117, v227 offset:19312
	ds_write_b16 v117, v228 offset:19584
	ds_write_b16_d16_hi v117, v228 offset:19856
	ds_write_b16 v117, v229 offset:20128
	ds_write_b16_d16_hi v117, v229 offset:20400
	ds_write_b16 v117, v230 offset:20672
	ds_write_b16_d16_hi v117, v230 offset:20944
	ds_write_b16 v117, v231 offset:21216
	ds_write_b16_d16_hi v117, v231 offset:21488
	s_waitcnt lgkmcnt(0)
	s_barrier
	ds_read_b128 v[88:91], v118 offset:17408
	ds_read_b128 v[92:95], v118 offset:17440
	ds_read_b128 v[96:99], v118 offset:17472
	ds_read_b128 v[100:103], v118 offset:17504
	s_waitcnt vmcnt(24) lgkmcnt(3)
	v_mfma_f32_32x32x16_bf16 v[0:15], v[88:91], v[120:123], 0
	s_waitcnt lgkmcnt(2)
	v_mfma_f32_32x32x16_bf16 v[0:15], v[92:95], v[124:127], v[0:15]
	s_waitcnt lgkmcnt(1)
	v_mfma_f32_32x32x16_bf16 v[0:15], v[96:99], v[128:131], v[0:15]
	s_waitcnt lgkmcnt(0)
	v_mfma_f32_32x32x16_bf16 v[0:15], v[100:103], v[132:135], v[0:15]
	s_cmp_lt_u32 s20, 0x100
	s_cbranch_scc1 .Lp3_half1
	ds_read_b128 v[88:91], v118 offset:17536
	ds_read_b128 v[92:95], v118 offset:17568
	ds_read_b128 v[96:99], v118 offset:17600
	ds_read_b128 v[100:103], v118 offset:17632
	s_waitcnt vmcnt(20)
	s_waitcnt lgkmcnt(3)
	v_mfma_f32_32x32x16_bf16 v[0:15], v[88:91], v[136:139], v[0:15]
	s_waitcnt lgkmcnt(2)
	v_mfma_f32_32x32x16_bf16 v[0:15], v[92:95], v[140:143], v[0:15]
	s_waitcnt lgkmcnt(1)
	v_mfma_f32_32x32x16_bf16 v[0:15], v[96:99], v[144:147], v[0:15]
	s_waitcnt lgkmcnt(0)
	v_mfma_f32_32x32x16_bf16 v[0:15], v[100:103], v[148:151], v[0:15]
.Lp3_half1:
	s_lshr_b32 s21, s39, 3
	s_and_b32 s22, s39, 7
	s_lshl_b32 s24, s21, 18
	s_lshl_b32 s25, s22, 7
	s_add_u32 s24, s24, s25
	s_add_u32 s24, s24, 0x14a00000
	s_add_u32 s48, s8, s24
	s_addc_u32 s49, s9, 0
	s_waitcnt vmcnt(15)
	v_lshlrev_b32_e32 v200, 16, v80
	v_and_b32_e32 v201, s38, v80
	v_lshlrev_b32_e32 v202, 16, v81
	v_and_b32_e32 v203, s38, v81
	v_lshlrev_b32_e32 v204, 16, v82
	v_and_b32_e32 v205, s38, v82
	v_lshlrev_b32_e32 v206, 16, v83
	v_and_b32_e32 v207, s38, v83
	v_lshlrev_b32_e32 v208, 16, v84
	v_and_b32_e32 v209, s38, v84
	v_lshlrev_b32_e32 v210, 16, v85
	v_and_b32_e32 v211, s38, v85
	v_lshlrev_b32_e32 v212, 16, v86
	v_and_b32_e32 v213, s38, v86
	v_lshlrev_b32_e32 v214, 16, v87
	v_and_b32_e32 v215, s38, v87
	s_nop 7
	v_pk_add_f32 v[0:1], v[0:1], v[34:35] op_sel_hi:[1,0]
	v_pk_add_f32 v[2:3], v[2:3], v[34:35] op_sel_hi:[1,0]
	v_pk_add_f32 v[4:5], v[4:5], v[34:35] op_sel_hi:[1,0]
	v_pk_add_f32 v[6:7], v[6:7], v[34:35] op_sel_hi:[1,0]
	v_pk_add_f32 v[8:9], v[8:9], v[34:35] op_sel_hi:[1,0]
	v_pk_add_f32 v[10:11], v[10:11], v[34:35] op_sel_hi:[1,0]
	v_pk_add_f32 v[12:13], v[12:13], v[34:35] op_sel_hi:[1,0]
	v_pk_add_f32 v[14:15], v[14:15], v[34:35] op_sel_hi:[1,0]
	v_pk_mul_f32 v[0:1], v[0:1], v[200:201]
	v_pk_mul_f32 v[2:3], v[2:3], v[202:203]
	v_pk_mul_f32 v[4:5], v[4:5], v[204:205]
	v_pk_mul_f32 v[6:7], v[6:7], v[206:207]
	v_pk_mul_f32 v[8:9], v[8:9], v[208:209]
	v_pk_mul_f32 v[10:11], v[10:11], v[210:211]
	v_pk_mul_f32 v[12:13], v[12:13], v[212:213]
	v_pk_mul_f32 v[14:15], v[14:15], v[214:215]
	v_cvt_pk_bf16_f32 v224, v0, v1
	v_cvt_pk_bf16_f32 v225, v2, v3
	v_cvt_pk_bf16_f32 v226, v4, v5
	v_cvt_pk_bf16_f32 v227, v6, v7
	v_cvt_pk_bf16_f32 v228, v8, v9
	v_cvt_pk_bf16_f32 v229, v10, v11
	v_cvt_pk_bf16_f32 v230, v12, v13
	v_cvt_pk_bf16_f32 v231, v14, v15
	global_store_dwordx2 v116, v[224:225], s[48:49]
	global_store_dwordx2 v116, v[226:227], s[48:49] offset:16
	global_store_dwordx2 v116, v[228:229], s[48:49] offset:32
	global_store_dwordx2 v116, v[230:231], s[48:49] offset:48
	s_add_u32 s45, s45, 1
	s_add_u32 s39, s39, s19
	s_branch .Lp3_body0
; #define LAS __attribute__((address_space(3)))
; __device__ __forceinline__ unsigned pk2(float lo, float hi) { f32x2_t v = {lo, hi}; bf16x2_t b = __builtin_convertvector(v, bf16x2_t); return __builtin_bit_cast(unsigned, b); }
; __device__ __forceinline__ float bf_lo(unsigned u) { return __uint_as_float(u << 16); }
; __device__ __forceinline__ float bf_hi(unsigned u) { return __uint_as_float(u & 0xffff0000u); }
; __global__ void __launch_bounds__(512, 2) mega_fwd(Args a) {
;     ...
;             {
;                 float xv[16];
;                 xv[0] = bf_lo(r0.x); xv[1] = bf_hi(r0.x); xv[2] = bf_lo(r0.y); xv[3] = bf_hi(r0.y); xv[4] = bf_lo(r0.z); xv[5] = bf_hi(r0.z); xv[6] = bf_lo(r0.w); xv[7] = bf_hi(r0.w);
;                 xv[8] = bf_lo(r1.x); xv[9] = bf_hi(r1.x); xv[10] = bf_lo(r1.y); xv[11] = bf_hi(r1.y); xv[12] = bf_lo(r1.z); xv[13] = bf_hi(r1.z); xv[14] = bf_lo(r1.w); xv[15] = bf_hi(r1.w);
;                 float sm = 0.f;
; #pragma unroll
;                 for (int e = 0; e < 16; ++e) sm += xv[e];
;                 sm += __shfl_xor(sm, 1); sm += __shfl_xor(sm, 2);
;                 const float mu = sm * (1.0f / 64.0f); float q = 0.f;
; #pragma unroll
;                 for (int e = 0; e < 16; ++e) { xv[e] -= mu; q += xv[e] * xv[e]; }
;                 q += __shfl_xor(q, 1); q += __shfl_xor(q, 2);
;                 const float rstd = rsqrtf(q * (1.0f / 64.0f) + EPS);
; #pragma unroll
;                 for (int e = 0; e < 16; ++e) { const float y = xv[e] * rstd * lgv[e >> 2][e & 3] + lbv[e >> 2][e & 3]; VLT[(16 * qd + e) * VLP + jt] = (bf16_t)(pk2(y, 0.f) & 0xffffu); }
;     ...
;             __syncthreads();
;             {
;                 f32x16 acc;
; #pragma unroll
;                 for (int r = 0; r < 16; ++r) acc[r] = 0.f;
;                 const LAS bf16_t* vl = VLT + (32 * dblk + r32) * VLP + 8 * hi;
; #pragma unroll
;                 for (int s = 0; s < 8; ++s) if (s < 4 || iblk >= 2) {
;                     const bf16x8 vf = *(const LAS bf16x8*)(vl + 16 * s);
;                     acc = __builtin_amdgcn_mfma_f32_32x32x16_bf16(vf, wf[s], acc, 0, 0, 0);
;                 }
.Lp3_last0:
	s_and_b32 s22, s39, 7
	s_lshl_b32 s22, s22, 8
	v_add_u32_e32 v232, s22, v119
	ds_read_b128 v[152:155], v232
	ds_read_b128 v[156:159], v232 offset:16
	ds_read_b128 v[160:163], v232 offset:32
	ds_read_b128 v[164:167], v232 offset:48
	ds_read_b128 v[168:171], v232 offset:2048
	ds_read_b128 v[172:175], v232 offset:2064
	ds_read_b128 v[176:179], v232 offset:2080
	ds_read_b128 v[180:183], v232 offset:2096
	s_waitcnt vmcnt(14)
	v_lshlrev_b32_e32 v200, 16, v16
	v_and_b32_e32 v201, s38, v16
	v_lshlrev_b32_e32 v202, 16, v17
	v_and_b32_e32 v203, s38, v17
	v_lshlrev_b32_e32 v204, 16, v18
	v_and_b32_e32 v205, s38, v18
	v_lshlrev_b32_e32 v206, 16, v19
	v_and_b32_e32 v207, s38, v19
	s_waitcnt vmcnt(13)
	v_lshlrev_b32_e32 v208, 16, v20
	v_and_b32_e32 v209, s38, v20
	v_lshlrev_b32_e32 v210, 16, v21
	v_and_b32_e32 v211, s38, v21
	v_lshlrev_b32_e32 v212, 16, v22
	v_and_b32_e32 v213, s38, v22
	v_lshlrev_b32_e32 v214, 16, v23
	v_and_b32_e32 v215, s38, v23
	v_pk_add_f32 v[216:217], v[200:201], v[202:203]
	v_pk_add_f32 v[218:219], v[204:205], v[206:207]
	v_pk_add_f32 v[220:221], v[208:209], v[210:211]
	v_pk_add_f32 v[222:223], v[212:213], v[214:215]
	v_pk_add_f32 v[216:217], v[216:217], v[218:219]
	v_pk_add_f32 v[220:221], v[220:221], v[222:223]
	v_pk_add_f32 v[216:217], v[216:217], v[220:221]
	v_add_f32_e32 v216, v216, v217
	s_nop 1
	v_add_f32_dpp v217, v216, v216 quad_perm:[1,0,3,2] row_mask:0xf bank_mask:0xf
	s_nop 1
	v_add_f32_dpp v216, v217, v217 quad_perm:[2,3,0,1] row_mask:0xf bank_mask:0xf
	v_mul_f32_e32 v216, 0xbc800000, v216
	v_pk_add_f32 v[200:201], v[200:201], v[216:217] op_sel_hi:[1,0]
	v_pk_add_f32 v[202:203], v[202:203], v[216:217] op_sel_hi:[1,0]
	v_pk_add_f32 v[204:205], v[204:205], v[216:217] op_sel_hi:[1,0]
	v_pk_add_f32 v[206:207], v[206:207], v[216:217] op_sel_hi:[1,0]
	v_pk_add_f32 v[208:209], v[208:209], v[216:217] op_sel_hi:[1,0]
	v_pk_add_f32 v[210:211], v[210:211], v[216:217] op_sel_hi:[1,0]
	v_pk_add_f32 v[212:213], v[212:213], v[216:217] op_sel_hi:[1,0]
	v_pk_add_f32 v[214:215], v[214:215], v[216:217] op_sel_hi:[1,0]
	v_pk_mul_f32 v[218:219], v[200:201], v[200:201]
	v_pk_mul_f32 v[220:221], v[202:203], v[202:203]
	v_pk_fma_f32 v[218:219], v[204:205], v[204:205], v[218:219]
	v_pk_fma_f32 v[220:221], v[206:207], v[206:207], v[220:221]
	v_pk_fma_f32 v[218:219], v[208:209], v[208:209], v[218:219]
	v_pk_fma_f32 v[220:221], v[210:211], v[210:211], v[220:221]
	v_pk_fma_f32 v[218:219], v[212:213], v[212:213], v[218:219]
	v_pk_fma_f32 v[220:221], v[214:215], v[214:215], v[220:221]
	v_pk_add_f32 v[218:219], v[218:219], v[220:221]
	v_add_f32_e32 v218, v218, v219
	s_nop 1
	v_add_f32_dpp v219, v218, v218 quad_perm:[1,0,3,2] row_mask:0xf bank_mask:0xf
	s_nop 1
	v_add_f32_dpp v218, v219, v219 quad_perm:[2,3,0,1] row_mask:0xf bank_mask:0xf
	v_fmamk_f32 v218, v218, 0x3c800000, v111
	v_rsq_f32_e32 v218, v218
	s_nop 0
	v_pk_mul_f32 v[200:201], v[200:201], v[218:219] op_sel_hi:[1,0]
	v_pk_mul_f32 v[202:203], v[202:203], v[218:219] op_sel_hi:[1,0]
	v_pk_mul_f32 v[204:205], v[204:205], v[218:219] op_sel_hi:[1,0]
	v_pk_mul_f32 v[206:207], v[206:207], v[218:219] op_sel_hi:[1,0]
	v_pk_mul_f32 v[208:209], v[208:209], v[218:219] op_sel_hi:[1,0]
	v_pk_mul_f32 v[210:211], v[210:211], v[218:219] op_sel_hi:[1,0]
	v_pk_mul_f32 v[212:213], v[212:213], v[218:219] op_sel_hi:[1,0]
	v_pk_mul_f32 v[214:215], v[214:215], v[218:219] op_sel_hi:[1,0]
	s_waitcnt lgkmcnt(0)
	v_pk_fma_f32 v[200:201], v[200:201], v[152:153], v[168:169]
	v_pk_fma_f32 v[202:203], v[202:203], v[154:155], v[170:171]
	v_pk_fma_f32 v[204:205], v[204:205], v[156:157], v[172:173]
	v_pk_fma_f32 v[206:207], v[206:207], v[158:159], v[174:175]
	v_pk_fma_f32 v[208:209], v[208:209], v[160:161], v[176:177]
	v_pk_fma_f32 v[210:211], v[210:211], v[162:163], v[178:179]
	v_pk_fma_f32 v[212:213], v[212:213], v[164:165], v[180:181]
	v_pk_fma_f32 v[214:215], v[214:215], v[166:167], v[182:183]
	v_cvt_pk_bf16_f32 v224, v200, v201
	v_cvt_pk_bf16_f32 v225, v202, v203
	v_cvt_pk_bf16_f32 v226, v204, v205
	v_cvt_pk_bf16_f32 v227, v206, v207
	v_cvt_pk_bf16_f32 v228, v208, v209
	v_cvt_pk_bf16_f32 v229, v210, v211
	v_cvt_pk_bf16_f32 v230, v212, v213
	v_cvt_pk_bf16_f32 v231, v214, v215
	ds_write_b16 v117, v224 offset:0
	ds_write_b16_d16_hi v117, v224 offset:272
	ds_write_b16 v117, v225 offset:544
	ds_write_b16_d16_hi v117, v225 offset:816
	ds_write_b16 v117, v226 offset:1088
	ds_write_b16_d16_hi v117, v226 offset:1360
	ds_write_b16 v117, v227 offset:1632
	ds_write_b16_d16_hi v117, v227 offset:1904
	ds_write_b16 v117, v228 offset:2176
	ds_write_b16_d16_hi v117, v228 offset:2448
	ds_write_b16 v117, v229 offset:2720
	ds_write_b16_d16_hi v117, v229 offset:2992
	ds_write_b16 v117, v230 offset:3264
	ds_write_b16_d16_hi v117, v230 offset:3536
	ds_write_b16 v117, v231 offset:3808
	ds_write_b16_d16_hi v117, v231 offset:4080
	s_waitcnt lgkmcnt(0)
	s_barrier
	ds_read_b128 v[88:91], v118 offset:0
	ds_read_b128 v[92:95], v118 offset:32
	ds_read_b128 v[96:99], v118 offset:64
	ds_read_b128 v[100:103], v118 offset:96
	s_waitcnt vmcnt(9) lgkmcnt(3)
	v_mfma_f32_32x32x16_bf16 v[0:15], v[88:91], v[40:43], 0
	s_waitcnt lgkmcnt(2)
	v_mfma_f32_32x32x16_bf16 v[0:15], v[92:95], v[44:47], v[0:15]
	s_waitcnt lgkmcnt(1)
	v_mfma_f32_32x32x16_bf16 v[0:15], v[96:99], v[48:51], v[0:15]
	s_waitcnt lgkmcnt(0)
	v_mfma_f32_32x32x16_bf16 v[0:15], v[100:103], v[52:55], v[0:15]
	s_cmp_lt_u32 s20, 0x100
	s_cbranch_scc1 .Lp3_halfl0
	ds_read_b128 v[88:91], v118 offset:128
	ds_read_b128 v[92:95], v118 offset:160
	ds_read_b128 v[96:99], v118 offset:192
	ds_read_b128 v[100:103], v118 offset:224
	s_waitcnt vmcnt(5)
	s_waitcnt lgkmcnt(3)
	v_mfma_f32_32x32x16_bf16 v[0:15], v[88:91], v[56:59], v[0:15]
	s_waitcnt lgkmcnt(2)
	v_mfma_f32_32x32x16_bf16 v[0:15], v[92:95], v[60:63], v[0:15]
	s_waitcnt lgkmcnt(1)
	v_mfma_f32_32x32x16_bf16 v[0:15], v[96:99], v[64:67], v[0:15]
	s_waitcnt lgkmcnt(0)
	v_mfma_f32_32x32x16_bf16 v[0:15], v[100:103], v[68:71], v[0:15]
; __device__ __forceinline__ unsigned pk2(float lo, float hi) { f32x2_t v = {lo, hi}; bf16x2_t b = __builtin_convertvector(v, bf16x2_t); return __builtin_bit_cast(unsigned, b); }
; __device__ __forceinline__ float bf_lo(unsigned u) { return __uint_as_float(u << 16); }
; __device__ __forceinline__ float bf_hi(unsigned u) { return __uint_as_float(u & 0xffff0000u); }
; __global__ void __launch_bounds__(512, 2) mega_fwd(Args a) {
;     ...
;             {
;                 float xv[16];
;                 xv[0] = bf_lo(r0.x); xv[1] = bf_hi(r0.x); xv[2] = bf_lo(r0.y); xv[3] = bf_hi(r0.y); xv[4] = bf_lo(r0.z); xv[5] = bf_hi(r0.z); xv[6] = bf_lo(r0.w); xv[7] = bf_hi(r0.w);
;                 xv[8] = bf_lo(r1.x); xv[9] = bf_hi(r1.x); xv[10] = bf_lo(r1.y); xv[11] = bf_hi(r1.y); xv[12] = bf_lo(r1.z); xv[13] = bf_hi(r1.z); xv[14] = bf_lo(r1.w); xv[15] = bf_hi(r1.w);
;                 float sm = 0.f;
; #pragma unroll
;                 for (int e = 0; e < 16; ++e) sm += xv[e];
;                 sm += __shfl_xor(sm, 1); sm += __shfl_xor(sm, 2);
;                 const float mu = sm * (1.0f / 64.0f); float q = 0.f;
; #pragma unroll
;                 for (int e = 0; e < 16; ++e) { xv[e] -= mu; q += xv[e] * xv[e]; }
;                 q += __shfl_xor(q, 1); q += __shfl_xor(q, 2);
;                 const float rstd = rsqrtf(q * (1.0f / 64.0f) + EPS);
; #pragma unroll
;                 for (int e = 0; e < 16; ++e) { const float y = xv[e] * rstd * lgv[e >> 2][e & 3] + lbv[e >> 2][e & 3]; VLT[(16 * qd + e) * VLP + jt] = (bf16_t)(pk2(y, 0.f) & 0xffffu); }
;     ...
;                 bf16_t* op = AO + (t0 + itok) * DM + 512 + h * 64 + 32 * dblk + 4 * hi;
; #pragma unroll
;                 for (int g = 0; g < 4; ++g) {
;                     u32x2 w; w.x = pk2(bf_lo(uu[g].x) * (acc[4 * g] + bsp), bf_hi(uu[g].x) * (acc[4 * g + 1] + bsp)); w.y = pk2(bf_lo(uu[g].y) * (acc[4 * g + 2] + bsp), bf_hi(uu[g].y) * (acc[4 * g + 3] + bsp));
;                     *(u32x2*)(op + 8 * g) = w;
;                 }
.Lp3_halfl0:
	s_lshr_b32 s21, s39, 3
	s_and_b32 s22, s39, 7
	s_lshl_b32 s24, s21, 18
	s_lshl_b32 s25, s22, 7
	s_add_u32 s24, s24, s25
	s_add_u32 s24, s24, 0x14a00000
	s_add_u32 s48, s8, s24
	s_addc_u32 s49, s9, 0
	s_waitcnt vmcnt(0)
	v_lshlrev_b32_e32 v200, 16, v24
	v_and_b32_e32 v201, s38, v24
	v_lshlrev_b32_e32 v202, 16, v25
	v_and_b32_e32 v203, s38, v25
	v_lshlrev_b32_e32 v204, 16, v26
	v_and_b32_e32 v205, s38, v26
	v_lshlrev_b32_e32 v206, 16, v27
	v_and_b32_e32 v207, s38, v27
	v_lshlrev_b32_e32 v208, 16, v28
	v_and_b32_e32 v209, s38, v28
	v_lshlrev_b32_e32 v210, 16, v29
	v_and_b32_e32 v211, s38, v29
	v_lshlrev_b32_e32 v212, 16, v30
	v_and_b32_e32 v213, s38, v30
	v_lshlrev_b32_e32 v214, 16, v31
	v_and_b32_e32 v215, s38, v31
	s_nop 7
	v_pk_add_f32 v[0:1], v[0:1], v[32:33] op_sel_hi:[1,0]
	v_pk_add_f32 v[2:3], v[2:3], v[32:33] op_sel_hi:[1,0]
	v_pk_add_f32 v[4:5], v[4:5], v[32:33] op_sel_hi:[1,0]
	v_pk_add_f32 v[6:7], v[6:7], v[32:33] op_sel_hi:[1,0]
	v_pk_add_f32 v[8:9], v[8:9], v[32:33] op_sel_hi:[1,0]
	v_pk_add_f32 v[10:11], v[10:11], v[32:33] op_sel_hi:[1,0]
	v_pk_add_f32 v[12:13], v[12:13], v[32:33] op_sel_hi:[1,0]
	v_pk_add_f32 v[14:15], v[14:15], v[32:33] op_sel_hi:[1,0]
	v_pk_mul_f32 v[0:1], v[0:1], v[200:201]
	v_pk_mul_f32 v[2:3], v[2:3], v[202:203]
	v_pk_mul_f32 v[4:5], v[4:5], v[204:205]
	v_pk_mul_f32 v[6:7], v[6:7], v[206:207]
	v_pk_mul_f32 v[8:9], v[8:9], v[208:209]
	v_pk_mul_f32 v[10:11], v[10:11], v[210:211]
	v_pk_mul_f32 v[12:13], v[12:13], v[212:213]
	v_pk_mul_f32 v[14:15], v[14:15], v[214:215]
	v_cvt_pk_bf16_f32 v224, v0, v1
	v_cvt_pk_bf16_f32 v225, v2, v3
	v_cvt_pk_bf16_f32 v226, v4, v5
	v_cvt_pk_bf16_f32 v227, v6, v7
	v_cvt_pk_bf16_f32 v228, v8, v9
	v_cvt_pk_bf16_f32 v229, v10, v11
	v_cvt_pk_bf16_f32 v230, v12, v13
	v_cvt_pk_bf16_f32 v231, v14, v15
	global_store_dwordx2 v116, v[224:225], s[48:49]
	global_store_dwordx2 v116, v[226:227], s[48:49] offset:16
	global_store_dwordx2 v116, v[228:229], s[48:49] offset:32
	global_store_dwordx2 v116, v[230:231], s[48:49] offset:48
	s_branch .Lp3_done
.Lp3_last1:
	s_and_b32 s22, s39, 7
	s_lshl_b32 s22, s22, 8
	v_add_u32_e32 v232, s22, v119
	ds_read_b128 v[152:155], v232
	ds_read_b128 v[156:159], v232 offset:16
	ds_read_b128 v[160:163], v232 offset:32
	ds_read_b128 v[164:167], v232 offset:48
	ds_read_b128 v[168:171], v232 offset:2048
	ds_read_b128 v[172:175], v232 offset:2064
	ds_read_b128 v[176:179], v232 offset:2080
	ds_read_b128 v[180:183], v232 offset:2096
	s_waitcnt vmcnt(14)
	v_lshlrev_b32_e32 v200, 16, v72
	v_and_b32_e32 v201, s38, v72
	v_lshlrev_b32_e32 v202, 16, v73
	v_and_b32_e32 v203, s38, v73
	v_lshlrev_b32_e32 v204, 16, v74
	v_and_b32_e32 v205, s38, v74
	v_lshlrev_b32_e32 v206, 16, v75
	v_and_b32_e32 v207, s38, v75
	s_waitcnt vmcnt(13)
	v_lshlrev_b32_e32 v208, 16, v76
	v_and_b32_e32 v209, s38, v76
	v_lshlrev_b32_e32 v210, 16, v77
	v_and_b32_e32 v211, s38, v77
	v_lshlrev_b32_e32 v212, 16, v78
	v_and_b32_e32 v213, s38, v78
	v_lshlrev_b32_e32 v214, 16, v79
	v_and_b32_e32 v215, s38, v79
	v_pk_add_f32 v[216:217], v[200:201], v[202:203]
	v_pk_add_f32 v[218:219], v[204:205], v[206:207]
	v_pk_add_f32 v[220:221], v[208:209], v[210:211]
	v_pk_add_f32 v[222:223], v[212:213], v[214:215]
	v_pk_add_f32 v[216:217], v[216:217], v[218:219]
	v_pk_add_f32 v[220:221], v[220:221], v[222:223]
	v_pk_add_f32 v[216:217], v[216:217], v[220:221]
	v_add_f32_e32 v216, v216, v217
	s_nop 1
	v_add_f32_dpp v217, v216, v216 quad_perm:[1,0,3,2] row_mask:0xf bank_mask:0xf
	s_nop 1
	v_add_f32_dpp v216, v217, v217 quad_perm:[2,3,0,1] row_mask:0xf bank_mask:0xf
	v_mul_f32_e32 v216, 0xbc800000, v216
	v_pk_add_f32 v[200:201], v[200:201], v[216:217] op_sel_hi:[1,0]
	v_pk_add_f32 v[202:203], v[202:203], v[216:217] op_sel_hi:[1,0]
	v_pk_add_f32 v[204:205], v[204:205], v[216:217] op_sel_hi:[1,0]
	v_pk_add_f32 v[206:207], v[206:207], v[216:217] op_sel_hi:[1,0]
	v_pk_add_f32 v[208:209], v[208:209], v[216:217] op_sel_hi:[1,0]
	v_pk_add_f32 v[210:211], v[210:211], v[216:217] op_sel_hi:[1,0]
	v_pk_add_f32 v[212:213], v[212:213], v[216:217] op_sel_hi:[1,0]
	v_pk_add_f32 v[214:215], v[214:215], v[216:217] op_sel_hi:[1,0]
	v_pk_mul_f32 v[218:219], v[200:201], v[200:201]
	v_pk_mul_f32 v[220:221], v[202:203], v[202:203]
	v_pk_fma_f32 v[218:219], v[204:205], v[204:205], v[218:219]
	v_pk_fma_f32 v[220:221], v[206:207], v[206:207], v[220:221]
	v_pk_fma_f32 v[218:219], v[208:209], v[208:209], v[218:219]
	v_pk_fma_f32 v[220:221], v[210:211], v[210:211], v[220:221]
	v_pk_fma_f32 v[218:219], v[212:213], v[212:213], v[218:219]
	v_pk_fma_f32 v[220:221], v[214:215], v[214:215], v[220:221]
	v_pk_add_f32 v[218:219], v[218:219], v[220:221]
	v_add_f32_e32 v218, v218, v219
	s_nop 1
	v_add_f32_dpp v219, v218, v218 quad_perm:[1,0,3,2] row_mask:0xf bank_mask:0xf
	s_nop 1
	v_add_f32_dpp v218, v219, v219 quad_perm:[2,3,0,1] row_mask:0xf bank_mask:0xf
	v_fmamk_f32 v218, v218, 0x3c800000, v111
	v_rsq_f32_e32 v218, v218
	s_nop 0
	v_pk_mul_f32 v[200:201], v[200:201], v[218:219] op_sel_hi:[1,0]
	v_pk_mul_f32 v[202:203], v[202:203], v[218:219] op_sel_hi:[1,0]
	v_pk_mul_f32 v[204:205], v[204:205], v[218:219] op_sel_hi:[1,0]
	v_pk_mul_f32 v[206:207], v[206:207], v[218:219] op_sel_hi:[1,0]
	v_pk_mul_f32 v[208:209], v[208:209], v[218:219] op_sel_hi:[1,0]
	v_pk_mul_f32 v[210:211], v[210:211], v[218:219] op_sel_hi:[1,0]
	v_pk_mul_f32 v[212:213], v[212:213], v[218:219] op_sel_hi:[1,0]
	v_pk_mul_f32 v[214:215], v[214:215], v[218:219] op_sel_hi:[1,0]
	s_waitcnt lgkmcnt(0)
	v_pk_fma_f32 v[200:201], v[200:201], v[152:153], v[168:169]
	v_pk_fma_f32 v[202:203], v[202:203], v[154:155], v[170:171]
	v_pk_fma_f32 v[204:205], v[204:205], v[156:157], v[172:173]
	v_pk_fma_f32 v[206:207], v[206:207], v[158:159], v[174:175]
	v_pk_fma_f32 v[208:209], v[208:209], v[160:161], v[176:177]
	v_pk_fma_f32 v[210:211], v[210:211], v[162:163], v[178:179]
	v_pk_fma_f32 v[212:213], v[212:213], v[164:165], v[180:181]
	v_pk_fma_f32 v[214:215], v[214:215], v[166:167], v[182:183]
	v_cvt_pk_bf16_f32 v224, v200, v201
	v_cvt_pk_bf16_f32 v225, v202, v203
	v_cvt_pk_bf16_f32 v226, v204, v205
	v_cvt_pk_bf16_f32 v227, v206, v207
	v_cvt_pk_bf16_f32 v228, v208, v209
	v_cvt_pk_bf16_f32 v229, v210, v211
	v_cvt_pk_bf16_f32 v230, v212, v213
	v_cvt_pk_bf16_f32 v231, v214, v215
	ds_write_b16 v117, v224 offset:17408
	ds_write_b16_d16_hi v117, v224 offset:17680
	ds_write_b16 v117, v225 offset:17952
	ds_write_b16_d16_hi v117, v225 offset:18224
	ds_write_b16 v117, v226 offset:18496
	ds_write_b16_d16_hi v117, v226 offset:18768
	ds_write_b16 v117, v227 offset:19040
	ds_write_b16_d16_hi v117, v227 offset:19312
	ds_write_b16 v117, v228 offset:19584
	ds_write_b16_d16_hi v117, v228 offset:19856
	ds_write_b16 v117, v229 offset:20128
	ds_write_b16_d16_hi v117, v229 offset:20400
	ds_write_b16 v117, v230 offset:20672
	ds_write_b16_d16_hi v117, v230 offset:20944
	ds_write_b16 v117, v231 offset:21216
	ds_write_b16_d16_hi v117, v231 offset:21488
	s_waitcnt lgkmcnt(0)
	s_barrier
; #define LAS __attribute__((address_space(3)))
; __device__ __forceinline__ unsigned pk2(float lo, float hi) { f32x2_t v = {lo, hi}; bf16x2_t b = __builtin_convertvector(v, bf16x2_t); return __builtin_bit_cast(unsigned, b); }
; __device__ __forceinline__ float bf_lo(unsigned u) { return __uint_as_float(u << 16); }
; __device__ __forceinline__ float bf_hi(unsigned u) { return __uint_as_float(u & 0xffff0000u); }
; __global__ void __launch_bounds__(512, 2) mega_fwd(Args a) {
;     ...
;             __syncthreads();
;             {
;                 f32x16 acc;
; #pragma unroll
;                 for (int r = 0; r < 16; ++r) acc[r] = 0.f;
;                 const LAS bf16_t* vl = VLT + (32 * dblk + r32) * VLP + 8 * hi;
; #pragma unroll
;                 for (int s = 0; s < 8; ++s) if (s < 4 || iblk >= 2) {
;                     const bf16x8 vf = *(const LAS bf16x8*)(vl + 16 * s);
;                     acc = __builtin_amdgcn_mfma_f32_32x32x16_bf16(vf, wf[s], acc, 0, 0, 0);
;                 }
;                 bf16_t* op = AO + (t0 + itok) * DM + 512 + h * 64 + 32 * dblk + 4 * hi;
; #pragma unroll
;                 for (int g = 0; g < 4; ++g) {
;                     u32x2 w; w.x = pk2(bf_lo(uu[g].x) * (acc[4 * g] + bsp), bf_hi(uu[g].x) * (acc[4 * g + 1] + bsp)); w.y = pk2(bf_lo(uu[g].y) * (acc[4 * g + 2] + bsp), bf_hi(uu[g].y) * (acc[4 * g + 3] + bsp));
;                     *(u32x2*)(op + 8 * g) = w;
;                 }
;             }
;             __syncthreads();
	ds_read_b128 v[88:91], v118 offset:17408
	ds_read_b128 v[92:95], v118 offset:17440
	ds_read_b128 v[96:99], v118 offset:17472
	ds_read_b128 v[100:103], v118 offset:17504
	s_waitcnt vmcnt(9) lgkmcnt(3)
	v_mfma_f32_32x32x16_bf16 v[0:15], v[88:91], v[120:123], 0
	s_waitcnt lgkmcnt(2)
	v_mfma_f32_32x32x16_bf16 v[0:15], v[92:95], v[124:127], v[0:15]
	s_waitcnt lgkmcnt(1)
	v_mfma_f32_32x32x16_bf16 v[0:15], v[96:99], v[128:131], v[0:15]
	s_waitcnt lgkmcnt(0)
	v_mfma_f32_32x32x16_bf16 v[0:15], v[100:103], v[132:135], v[0:15]
	s_cmp_lt_u32 s20, 0x100
	s_cbranch_scc1 .Lp3_halfl1
	ds_read_b128 v[88:91], v118 offset:17536
	ds_read_b128 v[92:95], v118 offset:17568
	ds_read_b128 v[96:99], v118 offset:17600
	ds_read_b128 v[100:103], v118 offset:17632
	s_waitcnt vmcnt(5)
	s_waitcnt lgkmcnt(3)
	v_mfma_f32_32x32x16_bf16 v[0:15], v[88:91], v[136:139], v[0:15]
	s_waitcnt lgkmcnt(2)
	v_mfma_f32_32x32x16_bf16 v[0:15], v[92:95], v[140:143], v[0:15]
	s_waitcnt lgkmcnt(1)
	v_mfma_f32_32x32x16_bf16 v[0:15], v[96:99], v[144:147], v[0:15]
	s_waitcnt lgkmcnt(0)
	v_mfma_f32_32x32x16_bf16 v[0:15], v[100:103], v[148:151], v[0:15]
.Lp3_halfl1:
	s_lshr_b32 s21, s39, 3
	s_and_b32 s22, s39, 7
	s_lshl_b32 s24, s21, 18
	s_lshl_b32 s25, s22, 7
	s_add_u32 s24, s24, s25
	s_add_u32 s24, s24, 0x14a00000
	s_add_u32 s48, s8, s24
	s_addc_u32 s49, s9, 0
	s_waitcnt vmcnt(0)
	v_lshlrev_b32_e32 v200, 16, v80
	v_and_b32_e32 v201, s38, v80
	v_lshlrev_b32_e32 v202, 16, v81
	v_and_b32_e32 v203, s38, v81
	v_lshlrev_b32_e32 v204, 16, v82
	v_and_b32_e32 v205, s38, v82
	v_lshlrev_b32_e32 v206, 16, v83
	v_and_b32_e32 v207, s38, v83
	v_lshlrev_b32_e32 v208, 16, v84
	v_and_b32_e32 v209, s38, v84
	v_lshlrev_b32_e32 v210, 16, v85
	v_and_b32_e32 v211, s38, v85
	v_lshlrev_b32_e32 v212, 16, v86
	v_and_b32_e32 v213, s38, v86
	v_lshlrev_b32_e32 v214, 16, v87
	v_and_b32_e32 v215, s38, v87
	s_nop 7
	v_pk_add_f32 v[0:1], v[0:1], v[34:35] op_sel_hi:[1,0]
	v_pk_add_f32 v[2:3], v[2:3], v[34:35] op_sel_hi:[1,0]
	v_pk_add_f32 v[4:5], v[4:5], v[34:35] op_sel_hi:[1,0]
	v_pk_add_f32 v[6:7], v[6:7], v[34:35] op_sel_hi:[1,0]
	v_pk_add_f32 v[8:9], v[8:9], v[34:35] op_sel_hi:[1,0]
	v_pk_add_f32 v[10:11], v[10:11], v[34:35] op_sel_hi:[1,0]
	v_pk_add_f32 v[12:13], v[12:13], v[34:35] op_sel_hi:[1,0]
	v_pk_add_f32 v[14:15], v[14:15], v[34:35] op_sel_hi:[1,0]
	v_pk_mul_f32 v[0:1], v[0:1], v[200:201]
	v_pk_mul_f32 v[2:3], v[2:3], v[202:203]
	v_pk_mul_f32 v[4:5], v[4:5], v[204:205]
	v_pk_mul_f32 v[6:7], v[6:7], v[206:207]
	v_pk_mul_f32 v[8:9], v[8:9], v[208:209]
	v_pk_mul_f32 v[10:11], v[10:11], v[210:211]
	v_pk_mul_f32 v[12:13], v[12:13], v[212:213]
	v_pk_mul_f32 v[14:15], v[14:15], v[214:215]
	v_cvt_pk_bf16_f32 v224, v0, v1
	v_cvt_pk_bf16_f32 v225, v2, v3
	v_cvt_pk_bf16_f32 v226, v4, v5
	v_cvt_pk_bf16_f32 v227, v6, v7
	v_cvt_pk_bf16_f32 v228, v8, v9
	v_cvt_pk_bf16_f32 v229, v10, v11
	v_cvt_pk_bf16_f32 v230, v12, v13
	v_cvt_pk_bf16_f32 v231, v14, v15
	global_store_dwordx2 v116, v[224:225], s[48:49]
	global_store_dwordx2 v116, v[226:227], s[48:49] offset:16
	global_store_dwordx2 v116, v[228:229], s[48:49] offset:32
	global_store_dwordx2 v116, v[230:231], s[48:49] offset:48
.Lp3_done:
	s_barrier
